# scanner: one operand wait per two steps
# baseline (speedup 1.0000x reference)
.LBB0_787:
	s_and_saveexec_b64 s[0:1], s[8:9]
	s_xor_b64 s[36:37], exec, s[0:1]
	s_cbranch_execz .LBB0_791
	s_and_saveexec_b64 s[44:45], s[26:27]
	s_cbranch_execz .LBB0_790
	s_and_b32 s0, s54, 1
	s_mul_i32 s1, s0, 0xc000
	s_lshl_b32 s4, s30, 2
	v_add_u32_e32 v10, s1, v97
	s_add_i32 s1, s1, s4
	v_lshl_add_u32 v11, v95, 2, s1
	v_lshl_add_u32 v12, s0, 14, v102
	v_pk_fma_f32 v[4:5], v[60:61], v[64:65], v[56:57] op_sel_hi:[0,1,1]
	v_pk_fma_f32 v[6:7], v[60:61], v[66:67], v[58:59] op_sel_hi:[0,1,1]
	v_pk_mul_f32 v[80:81], v[4:5], v[80:81]
	v_pk_fma_f32 v[80:81], v[6:7], v[82:83], v[80:81]
	v_add_f32_e32 v80, v80, v81
	v_pk_mul_f32 v[76:77], v[76:77], v[2:3] op_sel_hi:[1,0]
	v_pk_mul_f32 v[78:79], v[78:79], v[2:3] op_sel_hi:[1,0]
	v_add_f32_dpp v80, v80, v80 quad_perm:[1,0,3,2] row_mask:0xf bank_mask:0xf bound_ctrl:1
	v_pk_fma_f32 v[76:77], v[4:5], v[68:69], v[76:77]
	v_pk_fma_f32 v[78:79], v[6:7], v[70:71], v[78:79]
	v_add_f32_dpp v80, v80, v80 quad_perm:[2,3,0,1] row_mask:0xf bank_mask:0xf bound_ctrl:1
	v_pk_mul_f32 v[52:53], v[52:53], v[4:5]
	v_pk_fma_f32 v[52:53], v[6:7], v[54:55], v[52:53]
	v_add_f32_dpp v80, v80, v80 row_half_mirror row_mask:0xf bank_mask:0xf bound_ctrl:1
	v_add_f32_e32 v9, v52, v53
	ds_read_b128 v[36:39], v10 offset:512
	ds_read2st64_b32 v[0:1], v11 offset0:5 offset1:11
	ds_read_b128 v[40:43], v10 offset:768
	ds_read_b128 v[28:31], v10 offset:0
	ds_read_b128 v[44:47], v10 offset:1024
	ds_read_b128 v[32:35], v10 offset:256
	ds_read_b128 v[56:59], v10 offset:2048
	ds_read_b128 v[60:63], v10 offset:2304
	ds_read_b128 v[48:51], v10 offset:1536
	ds_read_b128 v[64:67], v10 offset:2560
	ds_read_b128 v[52:55], v10 offset:1792
	v_add_f32_dpp v80, v80, v80 row_mirror row_mask:0xf bank_mask:0xf bound_ctrl:1
	v_pk_fma_f32 v[4:5], v[80:81], v[84:85], v[76:77] op_sel_hi:[0,1,1]
	v_pk_fma_f32 v[6:7], v[80:81], v[86:87], v[78:79] op_sel_hi:[0,1,1]
	v_pk_mul_f32 v[116:117], v[4:5], v[116:117]
	v_pk_fma_f32 v[116:117], v[6:7], v[118:119], v[116:117]
	v_add_f32_e32 v116, v116, v117
	v_pk_mul_f32 v[112:113], v[112:113], v[2:3] op_sel:[0,1] op_sel_hi:[1,1]
	v_pk_mul_f32 v[114:115], v[114:115], v[2:3] op_sel:[0,1] op_sel_hi:[1,1]
	v_add_f32_dpp v116, v116, v116 quad_perm:[1,0,3,2] row_mask:0xf bank_mask:0xf bound_ctrl:1
	v_pk_fma_f32 v[112:113], v[4:5], v[104:105], v[112:113]
	v_pk_fma_f32 v[114:115], v[6:7], v[106:107], v[114:115]
	v_add_f32_dpp v116, v116, v116 quad_perm:[2,3,0,1] row_mask:0xf bank_mask:0xf bound_ctrl:1
	v_pk_mul_f32 v[72:73], v[72:73], v[4:5]
	v_pk_fma_f32 v[72:73], v[6:7], v[74:75], v[72:73]
	v_add_f32_dpp v116, v116, v116 row_half_mirror row_mask:0xf bank_mask:0xf bound_ctrl:1
	v_add_f32_e32 v8, v72, v73
	ds_read_b128 v[76:79], v10 offset:3584
	ds_read2st64_b32 v[2:3], v11 offset0:17 offset1:23
	ds_read_b128 v[80:83], v10 offset:3840
	ds_read_b128 v[68:71], v10 offset:3072
	ds_read_b128 v[84:87], v10 offset:4096
	ds_read_b128 v[72:75], v10 offset:3328
	ds_write2st64_b32 v12, v9, v8 offset0:0 offset1:2
	v_add_f32_dpp v116, v116, v116 row_mirror row_mask:0xf bank_mask:0xf bound_ctrl:1
	v_pk_fma_f32 v[4:5], v[116:117], v[120:121], v[112:113] op_sel_hi:[0,1,1]
	v_pk_fma_f32 v[6:7], v[116:117], v[122:123], v[114:115] op_sel_hi:[0,1,1]
	s_waitcnt lgkmcnt(7)
	v_pk_mul_f32 v[40:41], v[4:5], v[40:41]
	v_pk_fma_f32 v[40:41], v[6:7], v[42:43], v[40:41]
	v_add_f32_e32 v40, v40, v41
	v_pk_mul_f32 v[36:37], v[36:37], v[0:1] op_sel_hi:[1,0]
	v_pk_mul_f32 v[38:39], v[38:39], v[0:1] op_sel_hi:[1,0]
	v_add_f32_dpp v40, v40, v40 quad_perm:[1,0,3,2] row_mask:0xf bank_mask:0xf bound_ctrl:1
	v_pk_fma_f32 v[36:37], v[4:5], v[28:29], v[36:37]
	v_pk_fma_f32 v[38:39], v[6:7], v[30:31], v[38:39]
	v_add_f32_dpp v40, v40, v40 quad_perm:[2,3,0,1] row_mask:0xf bank_mask:0xf bound_ctrl:1
	v_pk_mul_f32 v[108:109], v[108:109], v[4:5]
	v_pk_fma_f32 v[108:109], v[6:7], v[110:111], v[108:109]
	v_add_f32_dpp v40, v40, v40 row_half_mirror row_mask:0xf bank_mask:0xf bound_ctrl:1
	v_add_f32_e32 v9, v108, v109
	ds_read_b128 v[112:115], v10 offset:5120
	ds_read_b128 v[116:119], v10 offset:5376
	ds_read_b128 v[104:107], v10 offset:4608
	ds_read_b128 v[120:123], v10 offset:5632
	ds_read_b128 v[108:111], v10 offset:4864
	v_add_f32_dpp v40, v40, v40 row_mirror row_mask:0xf bank_mask:0xf bound_ctrl:1
	v_pk_fma_f32 v[4:5], v[40:41], v[44:45], v[36:37] op_sel_hi:[0,1,1]
	v_pk_fma_f32 v[6:7], v[40:41], v[46:47], v[38:39] op_sel_hi:[0,1,1]
	v_pk_mul_f32 v[60:61], v[4:5], v[60:61]
	v_pk_fma_f32 v[60:61], v[6:7], v[62:63], v[60:61]
	v_add_f32_e32 v60, v60, v61
	v_pk_mul_f32 v[56:57], v[56:57], v[0:1] op_sel:[0,1] op_sel_hi:[1,1]
	v_pk_mul_f32 v[58:59], v[58:59], v[0:1] op_sel:[0,1] op_sel_hi:[1,1]
	v_add_f32_dpp v60, v60, v60 quad_perm:[1,0,3,2] row_mask:0xf bank_mask:0xf bound_ctrl:1
	v_pk_fma_f32 v[56:57], v[4:5], v[48:49], v[56:57]
	v_pk_fma_f32 v[58:59], v[6:7], v[50:51], v[58:59]
	v_add_f32_dpp v60, v60, v60 quad_perm:[2,3,0,1] row_mask:0xf bank_mask:0xf bound_ctrl:1
	v_pk_mul_f32 v[32:33], v[32:33], v[4:5]
	v_pk_fma_f32 v[32:33], v[6:7], v[34:35], v[32:33]
	v_add_f32_dpp v60, v60, v60 row_half_mirror row_mask:0xf bank_mask:0xf bound_ctrl:1
	v_add_f32_e32 v8, v32, v33
	ds_read_b128 v[36:39], v10 offset:6656
	ds_read2st64_b32 v[0:1], v11 offset0:29 offset1:35
	ds_read_b128 v[40:43], v10 offset:6912
	ds_read_b128 v[28:31], v10 offset:6144
	ds_read_b128 v[44:47], v10 offset:7168
	ds_read_b128 v[32:35], v10 offset:6400
	ds_write2st64_b32 v12, v9, v8 offset0:4 offset1:6
	v_add_f32_dpp v60, v60, v60 row_mirror row_mask:0xf bank_mask:0xf bound_ctrl:1
	v_pk_fma_f32 v[4:5], v[60:61], v[64:65], v[56:57] op_sel_hi:[0,1,1]
	v_pk_fma_f32 v[6:7], v[60:61], v[66:67], v[58:59] op_sel_hi:[0,1,1]
	s_waitcnt lgkmcnt(7)
	v_pk_mul_f32 v[80:81], v[4:5], v[80:81]
	v_pk_fma_f32 v[80:81], v[6:7], v[82:83], v[80:81]
	v_add_f32_e32 v80, v80, v81
	v_pk_mul_f32 v[76:77], v[76:77], v[2:3] op_sel_hi:[1,0]
	v_pk_mul_f32 v[78:79], v[78:79], v[2:3] op_sel_hi:[1,0]
	v_add_f32_dpp v80, v80, v80 quad_perm:[1,0,3,2] row_mask:0xf bank_mask:0xf bound_ctrl:1
	v_pk_fma_f32 v[76:77], v[4:5], v[68:69], v[76:77]
	v_pk_fma_f32 v[78:79], v[6:7], v[70:71], v[78:79]
	v_add_f32_dpp v80, v80, v80 quad_perm:[2,3,0,1] row_mask:0xf bank_mask:0xf bound_ctrl:1
	v_pk_mul_f32 v[52:53], v[52:53], v[4:5]
	v_pk_fma_f32 v[52:53], v[6:7], v[54:55], v[52:53]
	v_add_f32_dpp v80, v80, v80 row_half_mirror row_mask:0xf bank_mask:0xf bound_ctrl:1
	v_add_f32_e32 v9, v52, v53
	ds_read_b128 v[56:59], v10 offset:8192
	ds_read_b128 v[60:63], v10 offset:8448
	ds_read_b128 v[48:51], v10 offset:7680
	ds_read_b128 v[64:67], v10 offset:8704
	ds_read_b128 v[52:55], v10 offset:7936
	v_add_f32_dpp v80, v80, v80 row_mirror row_mask:0xf bank_mask:0xf bound_ctrl:1
	v_pk_fma_f32 v[4:5], v[80:81], v[84:85], v[76:77] op_sel_hi:[0,1,1]
	v_pk_fma_f32 v[6:7], v[80:81], v[86:87], v[78:79] op_sel_hi:[0,1,1]
	v_pk_mul_f32 v[116:117], v[4:5], v[116:117]
	v_pk_fma_f32 v[116:117], v[6:7], v[118:119], v[116:117]
	v_add_f32_e32 v116, v116, v117
	v_pk_mul_f32 v[112:113], v[112:113], v[2:3] op_sel:[0,1] op_sel_hi:[1,1]
	v_pk_mul_f32 v[114:115], v[114:115], v[2:3] op_sel:[0,1] op_sel_hi:[1,1]
	v_add_f32_dpp v116, v116, v116 quad_perm:[1,0,3,2] row_mask:0xf bank_mask:0xf bound_ctrl:1
	v_pk_fma_f32 v[112:113], v[4:5], v[104:105], v[112:113]
	v_pk_fma_f32 v[114:115], v[6:7], v[106:107], v[114:115]
	v_add_f32_dpp v116, v116, v116 quad_perm:[2,3,0,1] row_mask:0xf bank_mask:0xf bound_ctrl:1
	v_pk_mul_f32 v[72:73], v[72:73], v[4:5]
	v_pk_fma_f32 v[72:73], v[6:7], v[74:75], v[72:73]
	v_add_f32_dpp v116, v116, v116 row_half_mirror row_mask:0xf bank_mask:0xf bound_ctrl:1
	v_add_f32_e32 v8, v72, v73
	ds_read_b128 v[76:79], v10 offset:9728
	ds_read2st64_b32 v[2:3], v11 offset0:41 offset1:47
	ds_read_b128 v[80:83], v10 offset:9984
	ds_read_b128 v[68:71], v10 offset:9216
	ds_read_b128 v[84:87], v10 offset:10240
	ds_read_b128 v[72:75], v10 offset:9472
	ds_write2st64_b32 v12, v9, v8 offset0:8 offset1:10
	v_add_f32_dpp v116, v116, v116 row_mirror row_mask:0xf bank_mask:0xf bound_ctrl:1
	v_pk_fma_f32 v[4:5], v[116:117], v[120:121], v[112:113] op_sel_hi:[0,1,1]
	v_pk_fma_f32 v[6:7], v[116:117], v[122:123], v[114:115] op_sel_hi:[0,1,1]
	s_waitcnt lgkmcnt(7)
	v_pk_mul_f32 v[40:41], v[4:5], v[40:41]
	v_pk_fma_f32 v[40:41], v[6:7], v[42:43], v[40:41]
	v_add_f32_e32 v40, v40, v41
	v_pk_mul_f32 v[36:37], v[36:37], v[0:1] op_sel_hi:[1,0]
	v_pk_mul_f32 v[38:39], v[38:39], v[0:1] op_sel_hi:[1,0]
	v_add_f32_dpp v40, v40, v40 quad_perm:[1,0,3,2] row_mask:0xf bank_mask:0xf bound_ctrl:1
	v_pk_fma_f32 v[36:37], v[4:5], v[28:29], v[36:37]
	v_pk_fma_f32 v[38:39], v[6:7], v[30:31], v[38:39]
	v_add_f32_dpp v40, v40, v40 quad_perm:[2,3,0,1] row_mask:0xf bank_mask:0xf bound_ctrl:1
	v_pk_mul_f32 v[108:109], v[108:109], v[4:5]
	v_pk_fma_f32 v[108:109], v[6:7], v[110:111], v[108:109]
	v_add_f32_dpp v40, v40, v40 row_half_mirror row_mask:0xf bank_mask:0xf bound_ctrl:1
	v_add_f32_e32 v9, v108, v109
	ds_read_b128 v[112:115], v10 offset:11264
	ds_read_b128 v[116:119], v10 offset:11520
	ds_read_b128 v[104:107], v10 offset:10752
	ds_read_b128 v[120:123], v10 offset:11776
	ds_read_b128 v[108:111], v10 offset:11008
	v_add_f32_dpp v40, v40, v40 row_mirror row_mask:0xf bank_mask:0xf bound_ctrl:1
	v_pk_fma_f32 v[4:5], v[40:41], v[44:45], v[36:37] op_sel_hi:[0,1,1]
	v_pk_fma_f32 v[6:7], v[40:41], v[46:47], v[38:39] op_sel_hi:[0,1,1]
	v_pk_mul_f32 v[60:61], v[4:5], v[60:61]
	v_pk_fma_f32 v[60:61], v[6:7], v[62:63], v[60:61]
	v_add_f32_e32 v60, v60, v61
	v_pk_mul_f32 v[56:57], v[56:57], v[0:1] op_sel:[0,1] op_sel_hi:[1,1]
	v_pk_mul_f32 v[58:59], v[58:59], v[0:1] op_sel:[0,1] op_sel_hi:[1,1]
	v_add_f32_dpp v60, v60, v60 quad_perm:[1,0,3,2] row_mask:0xf bank_mask:0xf bound_ctrl:1
	v_pk_fma_f32 v[56:57], v[4:5], v[48:49], v[56:57]
	v_pk_fma_f32 v[58:59], v[6:7], v[50:51], v[58:59]
	v_add_f32_dpp v60, v60, v60 quad_perm:[2,3,0,1] row_mask:0xf bank_mask:0xf bound_ctrl:1
	v_pk_mul_f32 v[32:33], v[32:33], v[4:5]
	v_pk_fma_f32 v[32:33], v[6:7], v[34:35], v[32:33]
	v_add_f32_dpp v60, v60, v60 row_half_mirror row_mask:0xf bank_mask:0xf bound_ctrl:1
	v_add_f32_e32 v8, v32, v33
	ds_read_b128 v[36:39], v10 offset:12800
	ds_read2st64_b32 v[0:1], v11 offset0:53 offset1:59
	ds_read_b128 v[40:43], v10 offset:13056
	ds_read_b128 v[28:31], v10 offset:12288
	ds_read_b128 v[44:47], v10 offset:13312
	ds_read_b128 v[32:35], v10 offset:12544
	ds_write2st64_b32 v12, v9, v8 offset0:12 offset1:14
	v_add_f32_dpp v60, v60, v60 row_mirror row_mask:0xf bank_mask:0xf bound_ctrl:1
	v_pk_fma_f32 v[4:5], v[60:61], v[64:65], v[56:57] op_sel_hi:[0,1,1]
	v_pk_fma_f32 v[6:7], v[60:61], v[66:67], v[58:59] op_sel_hi:[0,1,1]
	s_waitcnt lgkmcnt(7)
	v_pk_mul_f32 v[80:81], v[4:5], v[80:81]
	v_pk_fma_f32 v[80:81], v[6:7], v[82:83], v[80:81]
	v_add_f32_e32 v80, v80, v81
	v_pk_mul_f32 v[76:77], v[76:77], v[2:3] op_sel_hi:[1,0]
	v_pk_mul_f32 v[78:79], v[78:79], v[2:3] op_sel_hi:[1,0]
	v_add_f32_dpp v80, v80, v80 quad_perm:[1,0,3,2] row_mask:0xf bank_mask:0xf bound_ctrl:1
	v_pk_fma_f32 v[76:77], v[4:5], v[68:69], v[76:77]
	v_pk_fma_f32 v[78:79], v[6:7], v[70:71], v[78:79]
	v_add_f32_dpp v80, v80, v80 quad_perm:[2,3,0,1] row_mask:0xf bank_mask:0xf bound_ctrl:1
	v_pk_mul_f32 v[52:53], v[52:53], v[4:5]
	v_pk_fma_f32 v[52:53], v[6:7], v[54:55], v[52:53]
	v_add_f32_dpp v80, v80, v80 row_half_mirror row_mask:0xf bank_mask:0xf bound_ctrl:1
	v_add_f32_e32 v9, v52, v53
	ds_read_b128 v[56:59], v10 offset:14336
	ds_read_b128 v[60:63], v10 offset:14592
	ds_read_b128 v[48:51], v10 offset:13824
	ds_read_b128 v[64:67], v10 offset:14848
	ds_read_b128 v[52:55], v10 offset:14080
	v_add_f32_dpp v80, v80, v80 row_mirror row_mask:0xf bank_mask:0xf bound_ctrl:1
	v_pk_fma_f32 v[4:5], v[80:81], v[84:85], v[76:77] op_sel_hi:[0,1,1]
	v_pk_fma_f32 v[6:7], v[80:81], v[86:87], v[78:79] op_sel_hi:[0,1,1]
	v_pk_mul_f32 v[116:117], v[4:5], v[116:117]
	v_pk_fma_f32 v[116:117], v[6:7], v[118:119], v[116:117]
	v_add_f32_e32 v116, v116, v117
	v_pk_mul_f32 v[112:113], v[112:113], v[2:3] op_sel:[0,1] op_sel_hi:[1,1]
	v_pk_mul_f32 v[114:115], v[114:115], v[2:3] op_sel:[0,1] op_sel_hi:[1,1]
	v_add_f32_dpp v116, v116, v116 quad_perm:[1,0,3,2] row_mask:0xf bank_mask:0xf bound_ctrl:1
	v_pk_fma_f32 v[112:113], v[4:5], v[104:105], v[112:113]
	v_pk_fma_f32 v[114:115], v[6:7], v[106:107], v[114:115]
	v_add_f32_dpp v116, v116, v116 quad_perm:[2,3,0,1] row_mask:0xf bank_mask:0xf bound_ctrl:1
	v_pk_mul_f32 v[72:73], v[72:73], v[4:5]
	v_pk_fma_f32 v[72:73], v[6:7], v[74:75], v[72:73]
	v_add_f32_dpp v116, v116, v116 row_half_mirror row_mask:0xf bank_mask:0xf bound_ctrl:1
	v_add_f32_e32 v8, v72, v73
	ds_read_b128 v[76:79], v10 offset:15872
	ds_read2st64_b32 v[2:3], v11 offset0:65 offset1:71
	ds_read_b128 v[80:83], v10 offset:16128
	ds_read_b128 v[68:71], v10 offset:15360
	ds_read_b128 v[84:87], v10 offset:16384
	ds_read_b128 v[72:75], v10 offset:15616
	ds_write2st64_b32 v12, v9, v8 offset0:16 offset1:18
	v_add_f32_dpp v116, v116, v116 row_mirror row_mask:0xf bank_mask:0xf bound_ctrl:1
	v_pk_fma_f32 v[4:5], v[116:117], v[120:121], v[112:113] op_sel_hi:[0,1,1]
	v_pk_fma_f32 v[6:7], v[116:117], v[122:123], v[114:115] op_sel_hi:[0,1,1]
	s_waitcnt lgkmcnt(7)
	v_pk_mul_f32 v[40:41], v[4:5], v[40:41]
	v_pk_fma_f32 v[40:41], v[6:7], v[42:43], v[40:41]
	v_add_f32_e32 v40, v40, v41
	v_pk_mul_f32 v[36:37], v[36:37], v[0:1] op_sel_hi:[1,0]
	v_pk_mul_f32 v[38:39], v[38:39], v[0:1] op_sel_hi:[1,0]
	v_add_f32_dpp v40, v40, v40 quad_perm:[1,0,3,2] row_mask:0xf bank_mask:0xf bound_ctrl:1
	v_pk_fma_f32 v[36:37], v[4:5], v[28:29], v[36:37]
	v_pk_fma_f32 v[38:39], v[6:7], v[30:31], v[38:39]
	v_add_f32_dpp v40, v40, v40 quad_perm:[2,3,0,1] row_mask:0xf bank_mask:0xf bound_ctrl:1
	v_pk_mul_f32 v[108:109], v[108:109], v[4:5]
	v_pk_fma_f32 v[108:109], v[6:7], v[110:111], v[108:109]
	v_add_f32_dpp v40, v40, v40 row_half_mirror row_mask:0xf bank_mask:0xf bound_ctrl:1
	v_add_f32_e32 v9, v108, v109
	ds_read_b128 v[112:115], v10 offset:17408
	ds_read_b128 v[116:119], v10 offset:17664
	ds_read_b128 v[104:107], v10 offset:16896
	ds_read_b128 v[120:123], v10 offset:17920
	ds_read_b128 v[108:111], v10 offset:17152
	v_add_f32_dpp v40, v40, v40 row_mirror row_mask:0xf bank_mask:0xf bound_ctrl:1
	v_pk_fma_f32 v[4:5], v[40:41], v[44:45], v[36:37] op_sel_hi:[0,1,1]
	v_pk_fma_f32 v[6:7], v[40:41], v[46:47], v[38:39] op_sel_hi:[0,1,1]
	v_pk_mul_f32 v[60:61], v[4:5], v[60:61]
	v_pk_fma_f32 v[60:61], v[6:7], v[62:63], v[60:61]
	v_add_f32_e32 v60, v60, v61
	v_pk_mul_f32 v[56:57], v[56:57], v[0:1] op_sel:[0,1] op_sel_hi:[1,1]
	v_pk_mul_f32 v[58:59], v[58:59], v[0:1] op_sel:[0,1] op_sel_hi:[1,1]
	v_add_f32_dpp v60, v60, v60 quad_perm:[1,0,3,2] row_mask:0xf bank_mask:0xf bound_ctrl:1
	v_pk_fma_f32 v[56:57], v[4:5], v[48:49], v[56:57]
	v_pk_fma_f32 v[58:59], v[6:7], v[50:51], v[58:59]
	v_add_f32_dpp v60, v60, v60 quad_perm:[2,3,0,1] row_mask:0xf bank_mask:0xf bound_ctrl:1
	v_pk_mul_f32 v[32:33], v[32:33], v[4:5]
	v_pk_fma_f32 v[32:33], v[6:7], v[34:35], v[32:33]
	v_add_f32_dpp v60, v60, v60 row_half_mirror row_mask:0xf bank_mask:0xf bound_ctrl:1
	v_add_f32_e32 v8, v32, v33
	ds_read_b128 v[36:39], v10 offset:18944
	ds_read2st64_b32 v[0:1], v11 offset0:77 offset1:83
	ds_read_b128 v[40:43], v10 offset:19200
	ds_read_b128 v[28:31], v10 offset:18432
	ds_read_b128 v[44:47], v10 offset:19456
	ds_read_b128 v[32:35], v10 offset:18688
	ds_write2st64_b32 v12, v9, v8 offset0:20 offset1:22
	v_add_f32_dpp v60, v60, v60 row_mirror row_mask:0xf bank_mask:0xf bound_ctrl:1
	v_pk_fma_f32 v[4:5], v[60:61], v[64:65], v[56:57] op_sel_hi:[0,1,1]
	v_pk_fma_f32 v[6:7], v[60:61], v[66:67], v[58:59] op_sel_hi:[0,1,1]
	s_waitcnt lgkmcnt(7)
	v_pk_mul_f32 v[80:81], v[4:5], v[80:81]
	v_pk_fma_f32 v[80:81], v[6:7], v[82:83], v[80:81]
	v_add_f32_e32 v80, v80, v81
	v_pk_mul_f32 v[76:77], v[76:77], v[2:3] op_sel_hi:[1,0]
	v_pk_mul_f32 v[78:79], v[78:79], v[2:3] op_sel_hi:[1,0]
	v_add_f32_dpp v80, v80, v80 quad_perm:[1,0,3,2] row_mask:0xf bank_mask:0xf bound_ctrl:1
	v_pk_fma_f32 v[76:77], v[4:5], v[68:69], v[76:77]
	v_pk_fma_f32 v[78:79], v[6:7], v[70:71], v[78:79]
	v_add_f32_dpp v80, v80, v80 quad_perm:[2,3,0,1] row_mask:0xf bank_mask:0xf bound_ctrl:1
	v_pk_mul_f32 v[52:53], v[52:53], v[4:5]
	v_pk_fma_f32 v[52:53], v[6:7], v[54:55], v[52:53]
	v_add_f32_dpp v80, v80, v80 row_half_mirror row_mask:0xf bank_mask:0xf bound_ctrl:1
	v_add_f32_e32 v9, v52, v53
	ds_read_b128 v[56:59], v10 offset:20480
	ds_read_b128 v[60:63], v10 offset:20736
	ds_read_b128 v[48:51], v10 offset:19968
	ds_read_b128 v[64:67], v10 offset:20992
	ds_read_b128 v[52:55], v10 offset:20224
	v_add_f32_dpp v80, v80, v80 row_mirror row_mask:0xf bank_mask:0xf bound_ctrl:1
	v_pk_fma_f32 v[4:5], v[80:81], v[84:85], v[76:77] op_sel_hi:[0,1,1]
	v_pk_fma_f32 v[6:7], v[80:81], v[86:87], v[78:79] op_sel_hi:[0,1,1]
	v_pk_mul_f32 v[116:117], v[4:5], v[116:117]
	v_pk_fma_f32 v[116:117], v[6:7], v[118:119], v[116:117]
	v_add_f32_e32 v116, v116, v117
	v_pk_mul_f32 v[112:113], v[112:113], v[2:3] op_sel:[0,1] op_sel_hi:[1,1]
	v_pk_mul_f32 v[114:115], v[114:115], v[2:3] op_sel:[0,1] op_sel_hi:[1,1]
	v_add_f32_dpp v116, v116, v116 quad_perm:[1,0,3,2] row_mask:0xf bank_mask:0xf bound_ctrl:1
	v_pk_fma_f32 v[112:113], v[4:5], v[104:105], v[112:113]
	v_pk_fma_f32 v[114:115], v[6:7], v[106:107], v[114:115]
	v_add_f32_dpp v116, v116, v116 quad_perm:[2,3,0,1] row_mask:0xf bank_mask:0xf bound_ctrl:1
	v_pk_mul_f32 v[72:73], v[72:73], v[4:5]
	v_pk_fma_f32 v[72:73], v[6:7], v[74:75], v[72:73]
	v_add_f32_dpp v116, v116, v116 row_half_mirror row_mask:0xf bank_mask:0xf bound_ctrl:1
	v_add_f32_e32 v8, v72, v73
	ds_read_b128 v[76:79], v10 offset:22016
	ds_read2st64_b32 v[2:3], v11 offset0:89 offset1:95
	ds_read_b128 v[80:83], v10 offset:22272
	ds_read_b128 v[68:71], v10 offset:21504
	ds_read_b128 v[84:87], v10 offset:22528
	ds_read_b128 v[72:75], v10 offset:21760
	ds_write2st64_b32 v12, v9, v8 offset0:24 offset1:26
	v_add_f32_dpp v116, v116, v116 row_mirror row_mask:0xf bank_mask:0xf bound_ctrl:1
	v_pk_fma_f32 v[4:5], v[116:117], v[120:121], v[112:113] op_sel_hi:[0,1,1]
	v_pk_fma_f32 v[6:7], v[116:117], v[122:123], v[114:115] op_sel_hi:[0,1,1]
	s_waitcnt lgkmcnt(7)
	v_pk_mul_f32 v[40:41], v[4:5], v[40:41]
	v_pk_fma_f32 v[40:41], v[6:7], v[42:43], v[40:41]
	v_add_f32_e32 v40, v40, v41
	v_pk_mul_f32 v[36:37], v[36:37], v[0:1] op_sel_hi:[1,0]
	v_pk_mul_f32 v[38:39], v[38:39], v[0:1] op_sel_hi:[1,0]
	v_add_f32_dpp v40, v40, v40 quad_perm:[1,0,3,2] row_mask:0xf bank_mask:0xf bound_ctrl:1
	v_pk_fma_f32 v[36:37], v[4:5], v[28:29], v[36:37]
	v_pk_fma_f32 v[38:39], v[6:7], v[30:31], v[38:39]
	v_add_f32_dpp v40, v40, v40 quad_perm:[2,3,0,1] row_mask:0xf bank_mask:0xf bound_ctrl:1
	v_pk_mul_f32 v[108:109], v[108:109], v[4:5]
	v_pk_fma_f32 v[108:109], v[6:7], v[110:111], v[108:109]
	v_add_f32_dpp v40, v40, v40 row_half_mirror row_mask:0xf bank_mask:0xf bound_ctrl:1
	v_add_f32_e32 v9, v108, v109
	ds_read_b128 v[112:115], v10 offset:23552
	ds_read_b128 v[116:119], v10 offset:23808
	ds_read_b128 v[104:107], v10 offset:23040
	ds_read_b128 v[120:123], v10 offset:24064
	ds_read_b128 v[108:111], v10 offset:23296
	v_add_f32_dpp v40, v40, v40 row_mirror row_mask:0xf bank_mask:0xf bound_ctrl:1
	v_pk_fma_f32 v[4:5], v[40:41], v[44:45], v[36:37] op_sel_hi:[0,1,1]
	v_pk_fma_f32 v[6:7], v[40:41], v[46:47], v[38:39] op_sel_hi:[0,1,1]
	v_pk_mul_f32 v[60:61], v[4:5], v[60:61]
	v_pk_fma_f32 v[60:61], v[6:7], v[62:63], v[60:61]
	v_add_f32_e32 v60, v60, v61
	v_pk_mul_f32 v[56:57], v[56:57], v[0:1] op_sel:[0,1] op_sel_hi:[1,1]
	v_pk_mul_f32 v[58:59], v[58:59], v[0:1] op_sel:[0,1] op_sel_hi:[1,1]
	v_add_f32_dpp v60, v60, v60 quad_perm:[1,0,3,2] row_mask:0xf bank_mask:0xf bound_ctrl:1
	v_pk_fma_f32 v[56:57], v[4:5], v[48:49], v[56:57]
	v_pk_fma_f32 v[58:59], v[6:7], v[50:51], v[58:59]
	v_add_f32_dpp v60, v60, v60 quad_perm:[2,3,0,1] row_mask:0xf bank_mask:0xf bound_ctrl:1
	v_pk_mul_f32 v[32:33], v[32:33], v[4:5]
	v_pk_fma_f32 v[32:33], v[6:7], v[34:35], v[32:33]
	v_add_f32_dpp v60, v60, v60 row_half_mirror row_mask:0xf bank_mask:0xf bound_ctrl:1
	v_add_f32_e32 v8, v32, v33
	ds_read_b128 v[36:39], v10 offset:25088
	ds_read2st64_b32 v[0:1], v11 offset0:101 offset1:107
	ds_read_b128 v[40:43], v10 offset:25344
	ds_read_b128 v[28:31], v10 offset:24576
	ds_read_b128 v[44:47], v10 offset:25600
	ds_read_b128 v[32:35], v10 offset:24832
	ds_write2st64_b32 v12, v9, v8 offset0:28 offset1:30
	v_add_f32_dpp v60, v60, v60 row_mirror row_mask:0xf bank_mask:0xf bound_ctrl:1
	v_pk_fma_f32 v[4:5], v[60:61], v[64:65], v[56:57] op_sel_hi:[0,1,1]
	v_pk_fma_f32 v[6:7], v[60:61], v[66:67], v[58:59] op_sel_hi:[0,1,1]
	s_waitcnt lgkmcnt(7)
	v_pk_mul_f32 v[80:81], v[4:5], v[80:81]
	v_pk_fma_f32 v[80:81], v[6:7], v[82:83], v[80:81]
	v_add_f32_e32 v80, v80, v81
	v_pk_mul_f32 v[76:77], v[76:77], v[2:3] op_sel_hi:[1,0]
	v_pk_mul_f32 v[78:79], v[78:79], v[2:3] op_sel_hi:[1,0]
	v_add_f32_dpp v80, v80, v80 quad_perm:[1,0,3,2] row_mask:0xf bank_mask:0xf bound_ctrl:1
	v_pk_fma_f32 v[76:77], v[4:5], v[68:69], v[76:77]
	v_pk_fma_f32 v[78:79], v[6:7], v[70:71], v[78:79]
	v_add_f32_dpp v80, v80, v80 quad_perm:[2,3,0,1] row_mask:0xf bank_mask:0xf bound_ctrl:1
	v_pk_mul_f32 v[52:53], v[52:53], v[4:5]
	v_pk_fma_f32 v[52:53], v[6:7], v[54:55], v[52:53]
	v_add_f32_dpp v80, v80, v80 row_half_mirror row_mask:0xf bank_mask:0xf bound_ctrl:1
	v_add_f32_e32 v9, v52, v53
	ds_read_b128 v[56:59], v10 offset:26624
	ds_read_b128 v[60:63], v10 offset:26880
	ds_read_b128 v[48:51], v10 offset:26112
	ds_read_b128 v[64:67], v10 offset:27136
	ds_read_b128 v[52:55], v10 offset:26368
	v_add_f32_dpp v80, v80, v80 row_mirror row_mask:0xf bank_mask:0xf bound_ctrl:1
	v_pk_fma_f32 v[4:5], v[80:81], v[84:85], v[76:77] op_sel_hi:[0,1,1]
	v_pk_fma_f32 v[6:7], v[80:81], v[86:87], v[78:79] op_sel_hi:[0,1,1]
	v_pk_mul_f32 v[116:117], v[4:5], v[116:117]
	v_pk_fma_f32 v[116:117], v[6:7], v[118:119], v[116:117]
	v_add_f32_e32 v116, v116, v117
	v_pk_mul_f32 v[112:113], v[112:113], v[2:3] op_sel:[0,1] op_sel_hi:[1,1]
	v_pk_mul_f32 v[114:115], v[114:115], v[2:3] op_sel:[0,1] op_sel_hi:[1,1]
	v_add_f32_dpp v116, v116, v116 quad_perm:[1,0,3,2] row_mask:0xf bank_mask:0xf bound_ctrl:1
	v_pk_fma_f32 v[112:113], v[4:5], v[104:105], v[112:113]
	v_pk_fma_f32 v[114:115], v[6:7], v[106:107], v[114:115]
	v_add_f32_dpp v116, v116, v116 quad_perm:[2,3,0,1] row_mask:0xf bank_mask:0xf bound_ctrl:1
	v_pk_mul_f32 v[72:73], v[72:73], v[4:5]
	v_pk_fma_f32 v[72:73], v[6:7], v[74:75], v[72:73]
	v_add_f32_dpp v116, v116, v116 row_half_mirror row_mask:0xf bank_mask:0xf bound_ctrl:1
	v_add_f32_e32 v8, v72, v73
	ds_read_b128 v[76:79], v10 offset:28160
	ds_read2st64_b32 v[2:3], v11 offset0:113 offset1:119
	ds_read_b128 v[80:83], v10 offset:28416
	ds_read_b128 v[68:71], v10 offset:27648
	ds_read_b128 v[84:87], v10 offset:28672
	ds_read_b128 v[72:75], v10 offset:27904
	ds_write2st64_b32 v12, v9, v8 offset0:32 offset1:34
	v_add_f32_dpp v116, v116, v116 row_mirror row_mask:0xf bank_mask:0xf bound_ctrl:1
	v_pk_fma_f32 v[4:5], v[116:117], v[120:121], v[112:113] op_sel_hi:[0,1,1]
	v_pk_fma_f32 v[6:7], v[116:117], v[122:123], v[114:115] op_sel_hi:[0,1,1]
	s_waitcnt lgkmcnt(7)
	v_pk_mul_f32 v[40:41], v[4:5], v[40:41]
	v_pk_fma_f32 v[40:41], v[6:7], v[42:43], v[40:41]
	v_add_f32_e32 v40, v40, v41
	v_pk_mul_f32 v[36:37], v[36:37], v[0:1] op_sel_hi:[1,0]
	v_pk_mul_f32 v[38:39], v[38:39], v[0:1] op_sel_hi:[1,0]
	v_add_f32_dpp v40, v40, v40 quad_perm:[1,0,3,2] row_mask:0xf bank_mask:0xf bound_ctrl:1
	v_pk_fma_f32 v[36:37], v[4:5], v[28:29], v[36:37]
	v_pk_fma_f32 v[38:39], v[6:7], v[30:31], v[38:39]
	v_add_f32_dpp v40, v40, v40 quad_perm:[2,3,0,1] row_mask:0xf bank_mask:0xf bound_ctrl:1
	v_pk_mul_f32 v[108:109], v[108:109], v[4:5]
	v_pk_fma_f32 v[108:109], v[6:7], v[110:111], v[108:109]
	v_add_f32_dpp v40, v40, v40 row_half_mirror row_mask:0xf bank_mask:0xf bound_ctrl:1
	v_add_f32_e32 v9, v108, v109
	ds_read_b128 v[112:115], v10 offset:29696
	ds_read_b128 v[116:119], v10 offset:29952
	ds_read_b128 v[104:107], v10 offset:29184
	ds_read_b128 v[120:123], v10 offset:30208
	ds_read_b128 v[108:111], v10 offset:29440
	v_add_f32_dpp v40, v40, v40 row_mirror row_mask:0xf bank_mask:0xf bound_ctrl:1
	v_pk_fma_f32 v[4:5], v[40:41], v[44:45], v[36:37] op_sel_hi:[0,1,1]
	v_pk_fma_f32 v[6:7], v[40:41], v[46:47], v[38:39] op_sel_hi:[0,1,1]
	v_pk_mul_f32 v[60:61], v[4:5], v[60:61]
	v_pk_fma_f32 v[60:61], v[6:7], v[62:63], v[60:61]
	v_add_f32_e32 v60, v60, v61
	v_pk_mul_f32 v[56:57], v[56:57], v[0:1] op_sel:[0,1] op_sel_hi:[1,1]
	v_pk_mul_f32 v[58:59], v[58:59], v[0:1] op_sel:[0,1] op_sel_hi:[1,1]
	v_add_f32_dpp v60, v60, v60 quad_perm:[1,0,3,2] row_mask:0xf bank_mask:0xf bound_ctrl:1
	v_pk_fma_f32 v[56:57], v[4:5], v[48:49], v[56:57]
	v_pk_fma_f32 v[58:59], v[6:7], v[50:51], v[58:59]
	v_add_f32_dpp v60, v60, v60 quad_perm:[2,3,0,1] row_mask:0xf bank_mask:0xf bound_ctrl:1
	v_pk_mul_f32 v[32:33], v[32:33], v[4:5]
	v_pk_fma_f32 v[32:33], v[6:7], v[34:35], v[32:33]
	v_add_f32_dpp v60, v60, v60 row_half_mirror row_mask:0xf bank_mask:0xf bound_ctrl:1
	v_add_f32_e32 v8, v32, v33
	ds_read_b128 v[36:39], v10 offset:31232
	ds_read2st64_b32 v[0:1], v11 offset0:125 offset1:131
	ds_read_b128 v[40:43], v10 offset:31488
	ds_read_b128 v[28:31], v10 offset:30720
	ds_read_b128 v[44:47], v10 offset:31744
	ds_read_b128 v[32:35], v10 offset:30976
	ds_write2st64_b32 v12, v9, v8 offset0:36 offset1:38
	v_add_f32_dpp v60, v60, v60 row_mirror row_mask:0xf bank_mask:0xf bound_ctrl:1
	v_pk_fma_f32 v[4:5], v[60:61], v[64:65], v[56:57] op_sel_hi:[0,1,1]
	v_pk_fma_f32 v[6:7], v[60:61], v[66:67], v[58:59] op_sel_hi:[0,1,1]
	s_waitcnt lgkmcnt(7)
	v_pk_mul_f32 v[80:81], v[4:5], v[80:81]
	v_pk_fma_f32 v[80:81], v[6:7], v[82:83], v[80:81]
	v_add_f32_e32 v80, v80, v81
	v_pk_mul_f32 v[76:77], v[76:77], v[2:3] op_sel_hi:[1,0]
	v_pk_mul_f32 v[78:79], v[78:79], v[2:3] op_sel_hi:[1,0]
	v_add_f32_dpp v80, v80, v80 quad_perm:[1,0,3,2] row_mask:0xf bank_mask:0xf bound_ctrl:1
	v_pk_fma_f32 v[76:77], v[4:5], v[68:69], v[76:77]
	v_pk_fma_f32 v[78:79], v[6:7], v[70:71], v[78:79]
	v_add_f32_dpp v80, v80, v80 quad_perm:[2,3,0,1] row_mask:0xf bank_mask:0xf bound_ctrl:1
	v_pk_mul_f32 v[52:53], v[52:53], v[4:5]
	v_pk_fma_f32 v[52:53], v[6:7], v[54:55], v[52:53]
	v_add_f32_dpp v80, v80, v80 row_half_mirror row_mask:0xf bank_mask:0xf bound_ctrl:1
	v_add_f32_e32 v9, v52, v53
	ds_read_b128 v[56:59], v10 offset:32768
	ds_read_b128 v[60:63], v10 offset:33024
	ds_read_b128 v[48:51], v10 offset:32256
	ds_read_b128 v[64:67], v10 offset:33280
	ds_read_b128 v[52:55], v10 offset:32512
	v_add_f32_dpp v80, v80, v80 row_mirror row_mask:0xf bank_mask:0xf bound_ctrl:1
	v_pk_fma_f32 v[4:5], v[80:81], v[84:85], v[76:77] op_sel_hi:[0,1,1]
	v_pk_fma_f32 v[6:7], v[80:81], v[86:87], v[78:79] op_sel_hi:[0,1,1]
	v_pk_mul_f32 v[116:117], v[4:5], v[116:117]
	v_pk_fma_f32 v[116:117], v[6:7], v[118:119], v[116:117]
	v_add_f32_e32 v116, v116, v117
	v_pk_mul_f32 v[112:113], v[112:113], v[2:3] op_sel:[0,1] op_sel_hi:[1,1]
	v_pk_mul_f32 v[114:115], v[114:115], v[2:3] op_sel:[0,1] op_sel_hi:[1,1]
	v_add_f32_dpp v116, v116, v116 quad_perm:[1,0,3,2] row_mask:0xf bank_mask:0xf bound_ctrl:1
	v_pk_fma_f32 v[112:113], v[4:5], v[104:105], v[112:113]
	v_pk_fma_f32 v[114:115], v[6:7], v[106:107], v[114:115]
	v_add_f32_dpp v116, v116, v116 quad_perm:[2,3,0,1] row_mask:0xf bank_mask:0xf bound_ctrl:1
	v_pk_mul_f32 v[72:73], v[72:73], v[4:5]
	v_pk_fma_f32 v[72:73], v[6:7], v[74:75], v[72:73]
	v_add_f32_dpp v116, v116, v116 row_half_mirror row_mask:0xf bank_mask:0xf bound_ctrl:1
	v_add_f32_e32 v8, v72, v73
	ds_read_b128 v[76:79], v10 offset:34304
	ds_read2st64_b32 v[2:3], v11 offset0:137 offset1:143
	ds_read_b128 v[80:83], v10 offset:34560
	ds_read_b128 v[68:71], v10 offset:33792
	ds_read_b128 v[84:87], v10 offset:34816
	ds_read_b128 v[72:75], v10 offset:34048
	ds_write2st64_b32 v12, v9, v8 offset0:40 offset1:42
	v_add_f32_dpp v116, v116, v116 row_mirror row_mask:0xf bank_mask:0xf bound_ctrl:1
	v_pk_fma_f32 v[4:5], v[116:117], v[120:121], v[112:113] op_sel_hi:[0,1,1]
	v_pk_fma_f32 v[6:7], v[116:117], v[122:123], v[114:115] op_sel_hi:[0,1,1]
	s_waitcnt lgkmcnt(7)
	v_pk_mul_f32 v[40:41], v[4:5], v[40:41]
	v_pk_fma_f32 v[40:41], v[6:7], v[42:43], v[40:41]
	v_add_f32_e32 v40, v40, v41
	v_pk_mul_f32 v[36:37], v[36:37], v[0:1] op_sel_hi:[1,0]
	v_pk_mul_f32 v[38:39], v[38:39], v[0:1] op_sel_hi:[1,0]
	v_add_f32_dpp v40, v40, v40 quad_perm:[1,0,3,2] row_mask:0xf bank_mask:0xf bound_ctrl:1
	v_pk_fma_f32 v[36:37], v[4:5], v[28:29], v[36:37]
	v_pk_fma_f32 v[38:39], v[6:7], v[30:31], v[38:39]
	v_add_f32_dpp v40, v40, v40 quad_perm:[2,3,0,1] row_mask:0xf bank_mask:0xf bound_ctrl:1
	v_pk_mul_f32 v[108:109], v[108:109], v[4:5]
	v_pk_fma_f32 v[108:109], v[6:7], v[110:111], v[108:109]
	v_add_f32_dpp v40, v40, v40 row_half_mirror row_mask:0xf bank_mask:0xf bound_ctrl:1
	v_add_f32_e32 v9, v108, v109
	ds_read_b128 v[112:115], v10 offset:35840
	ds_read_b128 v[116:119], v10 offset:36096
	ds_read_b128 v[104:107], v10 offset:35328
	ds_read_b128 v[120:123], v10 offset:36352
	ds_read_b128 v[108:111], v10 offset:35584
	v_add_f32_dpp v40, v40, v40 row_mirror row_mask:0xf bank_mask:0xf bound_ctrl:1
	v_pk_fma_f32 v[4:5], v[40:41], v[44:45], v[36:37] op_sel_hi:[0,1,1]
	v_pk_fma_f32 v[6:7], v[40:41], v[46:47], v[38:39] op_sel_hi:[0,1,1]
	v_pk_mul_f32 v[60:61], v[4:5], v[60:61]
	v_pk_fma_f32 v[60:61], v[6:7], v[62:63], v[60:61]
	v_add_f32_e32 v60, v60, v61
	v_pk_mul_f32 v[56:57], v[56:57], v[0:1] op_sel:[0,1] op_sel_hi:[1,1]
	v_pk_mul_f32 v[58:59], v[58:59], v[0:1] op_sel:[0,1] op_sel_hi:[1,1]
	v_add_f32_dpp v60, v60, v60 quad_perm:[1,0,3,2] row_mask:0xf bank_mask:0xf bound_ctrl:1
	v_pk_fma_f32 v[56:57], v[4:5], v[48:49], v[56:57]
	v_pk_fma_f32 v[58:59], v[6:7], v[50:51], v[58:59]
	v_add_f32_dpp v60, v60, v60 quad_perm:[2,3,0,1] row_mask:0xf bank_mask:0xf bound_ctrl:1
	v_pk_mul_f32 v[32:33], v[32:33], v[4:5]
	v_pk_fma_f32 v[32:33], v[6:7], v[34:35], v[32:33]
	v_add_f32_dpp v60, v60, v60 row_half_mirror row_mask:0xf bank_mask:0xf bound_ctrl:1
	v_add_f32_e32 v8, v32, v33
	ds_read_b128 v[36:39], v10 offset:37376
	ds_read2st64_b32 v[0:1], v11 offset0:149 offset1:155
	ds_read_b128 v[40:43], v10 offset:37632
	ds_read_b128 v[28:31], v10 offset:36864
	ds_read_b128 v[44:47], v10 offset:37888
	ds_read_b128 v[32:35], v10 offset:37120
	ds_write2st64_b32 v12, v9, v8 offset0:44 offset1:46
	v_add_f32_dpp v60, v60, v60 row_mirror row_mask:0xf bank_mask:0xf bound_ctrl:1
	v_pk_fma_f32 v[4:5], v[60:61], v[64:65], v[56:57] op_sel_hi:[0,1,1]
	v_pk_fma_f32 v[6:7], v[60:61], v[66:67], v[58:59] op_sel_hi:[0,1,1]
	s_waitcnt lgkmcnt(7)
	v_pk_mul_f32 v[80:81], v[4:5], v[80:81]
	v_pk_fma_f32 v[80:81], v[6:7], v[82:83], v[80:81]
	v_add_f32_e32 v80, v80, v81
	v_pk_mul_f32 v[76:77], v[76:77], v[2:3] op_sel_hi:[1,0]
	v_pk_mul_f32 v[78:79], v[78:79], v[2:3] op_sel_hi:[1,0]
	v_add_f32_dpp v80, v80, v80 quad_perm:[1,0,3,2] row_mask:0xf bank_mask:0xf bound_ctrl:1
	v_pk_fma_f32 v[76:77], v[4:5], v[68:69], v[76:77]
	v_pk_fma_f32 v[78:79], v[6:7], v[70:71], v[78:79]
	v_add_f32_dpp v80, v80, v80 quad_perm:[2,3,0,1] row_mask:0xf bank_mask:0xf bound_ctrl:1
	v_pk_mul_f32 v[52:53], v[52:53], v[4:5]
	v_pk_fma_f32 v[52:53], v[6:7], v[54:55], v[52:53]
	v_add_f32_dpp v80, v80, v80 row_half_mirror row_mask:0xf bank_mask:0xf bound_ctrl:1
	v_add_f32_e32 v9, v52, v53
	ds_read_b128 v[56:59], v10 offset:38912
	ds_read_b128 v[60:63], v10 offset:39168
	ds_read_b128 v[48:51], v10 offset:38400
	ds_read_b128 v[64:67], v10 offset:39424
	ds_read_b128 v[52:55], v10 offset:38656
	v_add_f32_dpp v80, v80, v80 row_mirror row_mask:0xf bank_mask:0xf bound_ctrl:1
	v_pk_fma_f32 v[4:5], v[80:81], v[84:85], v[76:77] op_sel_hi:[0,1,1]
	v_pk_fma_f32 v[6:7], v[80:81], v[86:87], v[78:79] op_sel_hi:[0,1,1]
	v_pk_mul_f32 v[116:117], v[4:5], v[116:117]
	v_pk_fma_f32 v[116:117], v[6:7], v[118:119], v[116:117]
	v_add_f32_e32 v116, v116, v117
	v_pk_mul_f32 v[112:113], v[112:113], v[2:3] op_sel:[0,1] op_sel_hi:[1,1]
	v_pk_mul_f32 v[114:115], v[114:115], v[2:3] op_sel:[0,1] op_sel_hi:[1,1]
	v_add_f32_dpp v116, v116, v116 quad_perm:[1,0,3,2] row_mask:0xf bank_mask:0xf bound_ctrl:1
	v_pk_fma_f32 v[112:113], v[4:5], v[104:105], v[112:113]
	v_pk_fma_f32 v[114:115], v[6:7], v[106:107], v[114:115]
	v_add_f32_dpp v116, v116, v116 quad_perm:[2,3,0,1] row_mask:0xf bank_mask:0xf bound_ctrl:1
	v_pk_mul_f32 v[72:73], v[72:73], v[4:5]
	v_pk_fma_f32 v[72:73], v[6:7], v[74:75], v[72:73]
	v_add_f32_dpp v116, v116, v116 row_half_mirror row_mask:0xf bank_mask:0xf bound_ctrl:1
	v_add_f32_e32 v8, v72, v73
	ds_read_b128 v[76:79], v10 offset:40448
	ds_read2st64_b32 v[2:3], v11 offset0:161 offset1:167
	ds_read_b128 v[80:83], v10 offset:40704
	ds_read_b128 v[68:71], v10 offset:39936
	ds_read_b128 v[84:87], v10 offset:40960
	ds_read_b128 v[72:75], v10 offset:40192
	ds_write2st64_b32 v12, v9, v8 offset0:48 offset1:50
	v_add_f32_dpp v116, v116, v116 row_mirror row_mask:0xf bank_mask:0xf bound_ctrl:1
	v_pk_fma_f32 v[4:5], v[116:117], v[120:121], v[112:113] op_sel_hi:[0,1,1]
	v_pk_fma_f32 v[6:7], v[116:117], v[122:123], v[114:115] op_sel_hi:[0,1,1]
	s_waitcnt lgkmcnt(7)
	v_pk_mul_f32 v[40:41], v[4:5], v[40:41]
	v_pk_fma_f32 v[40:41], v[6:7], v[42:43], v[40:41]
	v_add_f32_e32 v40, v40, v41
	v_pk_mul_f32 v[36:37], v[36:37], v[0:1] op_sel_hi:[1,0]
	v_pk_mul_f32 v[38:39], v[38:39], v[0:1] op_sel_hi:[1,0]
	v_add_f32_dpp v40, v40, v40 quad_perm:[1,0,3,2] row_mask:0xf bank_mask:0xf bound_ctrl:1
	v_pk_fma_f32 v[36:37], v[4:5], v[28:29], v[36:37]
	v_pk_fma_f32 v[38:39], v[6:7], v[30:31], v[38:39]
	v_add_f32_dpp v40, v40, v40 quad_perm:[2,3,0,1] row_mask:0xf bank_mask:0xf bound_ctrl:1
	v_pk_mul_f32 v[108:109], v[108:109], v[4:5]
	v_pk_fma_f32 v[108:109], v[6:7], v[110:111], v[108:109]
	v_add_f32_dpp v40, v40, v40 row_half_mirror row_mask:0xf bank_mask:0xf bound_ctrl:1
	v_add_f32_e32 v9, v108, v109
	ds_read_b128 v[112:115], v10 offset:41984
	ds_read_b128 v[116:119], v10 offset:42240
	ds_read_b128 v[104:107], v10 offset:41472
	ds_read_b128 v[120:123], v10 offset:42496
	ds_read_b128 v[108:111], v10 offset:41728
	v_add_f32_dpp v40, v40, v40 row_mirror row_mask:0xf bank_mask:0xf bound_ctrl:1
	v_pk_fma_f32 v[4:5], v[40:41], v[44:45], v[36:37] op_sel_hi:[0,1,1]
	v_pk_fma_f32 v[6:7], v[40:41], v[46:47], v[38:39] op_sel_hi:[0,1,1]
	v_pk_mul_f32 v[60:61], v[4:5], v[60:61]
	v_pk_fma_f32 v[60:61], v[6:7], v[62:63], v[60:61]
	v_add_f32_e32 v60, v60, v61
	v_pk_mul_f32 v[56:57], v[56:57], v[0:1] op_sel:[0,1] op_sel_hi:[1,1]
	v_pk_mul_f32 v[58:59], v[58:59], v[0:1] op_sel:[0,1] op_sel_hi:[1,1]
	v_add_f32_dpp v60, v60, v60 quad_perm:[1,0,3,2] row_mask:0xf bank_mask:0xf bound_ctrl:1
	v_pk_fma_f32 v[56:57], v[4:5], v[48:49], v[56:57]
	v_pk_fma_f32 v[58:59], v[6:7], v[50:51], v[58:59]
	v_add_f32_dpp v60, v60, v60 quad_perm:[2,3,0,1] row_mask:0xf bank_mask:0xf bound_ctrl:1
	v_pk_mul_f32 v[32:33], v[32:33], v[4:5]
	v_pk_fma_f32 v[32:33], v[6:7], v[34:35], v[32:33]
	v_add_f32_dpp v60, v60, v60 row_half_mirror row_mask:0xf bank_mask:0xf bound_ctrl:1
	v_add_f32_e32 v8, v32, v33
	ds_read_b128 v[36:39], v10 offset:43520
	ds_read2st64_b32 v[0:1], v11 offset0:173 offset1:179
	ds_read_b128 v[40:43], v10 offset:43776
	ds_read_b128 v[28:31], v10 offset:43008
	ds_read_b128 v[44:47], v10 offset:44032
	ds_read_b128 v[32:35], v10 offset:43264
	ds_write2st64_b32 v12, v9, v8 offset0:52 offset1:54
	v_add_f32_dpp v60, v60, v60 row_mirror row_mask:0xf bank_mask:0xf bound_ctrl:1
	v_pk_fma_f32 v[4:5], v[60:61], v[64:65], v[56:57] op_sel_hi:[0,1,1]
	v_pk_fma_f32 v[6:7], v[60:61], v[66:67], v[58:59] op_sel_hi:[0,1,1]
	s_waitcnt lgkmcnt(7)
	v_pk_mul_f32 v[80:81], v[4:5], v[80:81]
	v_pk_fma_f32 v[80:81], v[6:7], v[82:83], v[80:81]
	v_add_f32_e32 v80, v80, v81
	v_pk_mul_f32 v[76:77], v[76:77], v[2:3] op_sel_hi:[1,0]
	v_pk_mul_f32 v[78:79], v[78:79], v[2:3] op_sel_hi:[1,0]
	v_add_f32_dpp v80, v80, v80 quad_perm:[1,0,3,2] row_mask:0xf bank_mask:0xf bound_ctrl:1
	v_pk_fma_f32 v[76:77], v[4:5], v[68:69], v[76:77]
	v_pk_fma_f32 v[78:79], v[6:7], v[70:71], v[78:79]
	v_add_f32_dpp v80, v80, v80 quad_perm:[2,3,0,1] row_mask:0xf bank_mask:0xf bound_ctrl:1
	v_pk_mul_f32 v[52:53], v[52:53], v[4:5]
	v_pk_fma_f32 v[52:53], v[6:7], v[54:55], v[52:53]
	v_add_f32_dpp v80, v80, v80 row_half_mirror row_mask:0xf bank_mask:0xf bound_ctrl:1
	v_add_f32_e32 v9, v52, v53
	ds_read_b128 v[56:59], v10 offset:45056
	ds_read_b128 v[60:63], v10 offset:45312
	ds_read_b128 v[48:51], v10 offset:44544
	ds_read_b128 v[64:67], v10 offset:45568
	ds_read_b128 v[52:55], v10 offset:44800
	v_add_f32_dpp v80, v80, v80 row_mirror row_mask:0xf bank_mask:0xf bound_ctrl:1
	v_pk_fma_f32 v[4:5], v[80:81], v[84:85], v[76:77] op_sel_hi:[0,1,1]
	v_pk_fma_f32 v[6:7], v[80:81], v[86:87], v[78:79] op_sel_hi:[0,1,1]
	v_pk_mul_f32 v[116:117], v[4:5], v[116:117]
	v_pk_fma_f32 v[116:117], v[6:7], v[118:119], v[116:117]
	v_add_f32_e32 v116, v116, v117
	v_pk_mul_f32 v[112:113], v[112:113], v[2:3] op_sel:[0,1] op_sel_hi:[1,1]
	v_pk_mul_f32 v[114:115], v[114:115], v[2:3] op_sel:[0,1] op_sel_hi:[1,1]
	v_add_f32_dpp v116, v116, v116 quad_perm:[1,0,3,2] row_mask:0xf bank_mask:0xf bound_ctrl:1
	v_pk_fma_f32 v[112:113], v[4:5], v[104:105], v[112:113]
	v_pk_fma_f32 v[114:115], v[6:7], v[106:107], v[114:115]
	v_add_f32_dpp v116, v116, v116 quad_perm:[2,3,0,1] row_mask:0xf bank_mask:0xf bound_ctrl:1
	v_pk_mul_f32 v[72:73], v[72:73], v[4:5]
	v_pk_fma_f32 v[72:73], v[6:7], v[74:75], v[72:73]
	v_add_f32_dpp v116, v116, v116 row_half_mirror row_mask:0xf bank_mask:0xf bound_ctrl:1
	v_add_f32_e32 v8, v72, v73
	ds_read_b128 v[76:79], v10 offset:46592
	ds_read2st64_b32 v[2:3], v11 offset0:185 offset1:191
	ds_read_b128 v[80:83], v10 offset:46848
	ds_read_b128 v[68:71], v10 offset:46080
	ds_read_b128 v[84:87], v10 offset:47104
	ds_read_b128 v[72:75], v10 offset:46336
	ds_write2st64_b32 v12, v9, v8 offset0:56 offset1:58
	v_add_f32_dpp v116, v116, v116 row_mirror row_mask:0xf bank_mask:0xf bound_ctrl:1
	v_pk_fma_f32 v[4:5], v[116:117], v[120:121], v[112:113] op_sel_hi:[0,1,1]
	v_pk_fma_f32 v[6:7], v[116:117], v[122:123], v[114:115] op_sel_hi:[0,1,1]
	s_waitcnt lgkmcnt(7)
	v_pk_mul_f32 v[40:41], v[4:5], v[40:41]
	v_pk_fma_f32 v[40:41], v[6:7], v[42:43], v[40:41]
	v_add_f32_e32 v40, v40, v41
	v_pk_mul_f32 v[36:37], v[36:37], v[0:1] op_sel_hi:[1,0]
	v_pk_mul_f32 v[38:39], v[38:39], v[0:1] op_sel_hi:[1,0]
	v_add_f32_dpp v40, v40, v40 quad_perm:[1,0,3,2] row_mask:0xf bank_mask:0xf bound_ctrl:1
	v_pk_fma_f32 v[36:37], v[4:5], v[28:29], v[36:37]
	v_pk_fma_f32 v[38:39], v[6:7], v[30:31], v[38:39]
	v_add_f32_dpp v40, v40, v40 quad_perm:[2,3,0,1] row_mask:0xf bank_mask:0xf bound_ctrl:1
	v_pk_mul_f32 v[108:109], v[108:109], v[4:5]
	v_pk_fma_f32 v[108:109], v[6:7], v[110:111], v[108:109]
	v_add_f32_dpp v40, v40, v40 row_half_mirror row_mask:0xf bank_mask:0xf bound_ctrl:1
	v_add_f32_e32 v9, v108, v109
	ds_read_b128 v[112:115], v10 offset:48128
	ds_read_b128 v[116:119], v10 offset:48384
	ds_read_b128 v[104:107], v10 offset:47616
	ds_read_b128 v[120:123], v10 offset:48640
	ds_read_b128 v[108:111], v10 offset:47872
	v_add_f32_dpp v40, v40, v40 row_mirror row_mask:0xf bank_mask:0xf bound_ctrl:1
	v_pk_fma_f32 v[4:5], v[40:41], v[44:45], v[36:37] op_sel_hi:[0,1,1]
	v_pk_fma_f32 v[6:7], v[40:41], v[46:47], v[38:39] op_sel_hi:[0,1,1]
	v_pk_mul_f32 v[60:61], v[4:5], v[60:61]
	v_pk_fma_f32 v[60:61], v[6:7], v[62:63], v[60:61]
	v_add_f32_e32 v60, v60, v61
	v_pk_mul_f32 v[56:57], v[56:57], v[0:1] op_sel:[0,1] op_sel_hi:[1,1]
	v_pk_mul_f32 v[58:59], v[58:59], v[0:1] op_sel:[0,1] op_sel_hi:[1,1]
	v_add_f32_dpp v60, v60, v60 quad_perm:[1,0,3,2] row_mask:0xf bank_mask:0xf bound_ctrl:1
	v_pk_fma_f32 v[56:57], v[4:5], v[48:49], v[56:57]
	v_pk_fma_f32 v[58:59], v[6:7], v[50:51], v[58:59]
	v_add_f32_dpp v60, v60, v60 quad_perm:[2,3,0,1] row_mask:0xf bank_mask:0xf bound_ctrl:1
	v_pk_mul_f32 v[32:33], v[32:33], v[4:5]
	v_pk_fma_f32 v[32:33], v[6:7], v[34:35], v[32:33]
	v_add_f32_dpp v60, v60, v60 row_half_mirror row_mask:0xf bank_mask:0xf bound_ctrl:1
	v_add_f32_e32 v8, v32, v33
	ds_write2st64_b32 v12, v9, v8 offset0:60 offset1:62
	s_nop 0
	v_add_f32_dpp v60, v60, v60 row_mirror row_mask:0xf bank_mask:0xf bound_ctrl:1
